# v57 + MLA loop: first K-fragment ds_reads issued before the next tile's DMA block at the head of each half
# speedup vs baseline: 1.0052x; 1.0052x over previous
.LBB0_543:
	s_mov_b32 s23, s17
	s_mov_b32 s17, s0
	s_add_i32 s71, 0, 0x10000
	ds_read_b128 v[66:69], v174 offset:49152
	ds_read_b128 v[70:73], v174 offset:57344
	ds_read_b128 v[206:209], v176 offset:49152
	ds_read_b128 v[210:213], v176 offset:57344
	s_add_u32 s4, s38, s20
	s_addc_u32 s5, s39, s21
	s_add_u32 s24, s4, 0x149ec400
	s_addc_u32 s25, s5, 0
	s_mov_b32 m0, s90
	v_lshl_add_u64 v[254:255], v[246:247], 0, s[24:25]
	s_lshl_b32 s18, s22, 14
	global_load_lds_dwordx4 v[254:255], off
	s_add_u32 s24, s4, 0x14a0c400
	s_addc_u32 s25, s5, 0
	s_mov_b32 m0, s91
	v_lshl_add_u64 v[254:255], v[246:247], 0, s[24:25]
	s_add_i32 s1, s89, s18
	global_load_lds_dwordx4 v[254:255], off
	s_add_u32 s24, s4, 0x149ec500
	s_addc_u32 s25, s5, 0
	s_mov_b32 m0, s1
	v_lshl_add_u64 v[254:255], v[248:249], 0, s[24:25]
	global_load_lds_dwordx4 v[254:255], off
	s_add_u32 s24, s4, 0x14a0c500
	s_addc_u32 s25, s5, 0
	s_add_i32 m0, s1, 0x2000
	v_lshl_add_u64 v[254:255], v[248:249], 0, s[24:25]
	global_load_lds_dwordx4 v[254:255], off
	s_add_u32 s4, s38, s88
	s_addc_u32 s5, s39, s87
	s_add_u32 s4, s4, s36
	s_addc_u32 s5, s5, s37
	s_mov_b32 m0, s92
	v_lshl_add_u64 v[254:255], v[250:251], 0, s[4:5]
	global_load_lds_dwordx4 v[254:255], off
	v_fma_f32 v152, v74, s34, v146
	v_fma_f32 v153, v75, s34, v146
	v_fma_f32 v150, v76, s34, v146
	v_fma_f32 v151, v77, s34, v146
	v_fma_f32 v148, v78, s34, v146
	v_fma_f32 v149, v79, s34, v146
	v_fma_f32 v147, v81, s34, v146
	v_fma_f32 v146, v80, s34, v146
	v_exp_f32_e32 v229, v229
	v_exp_f32_e32 v231, v231
	v_exp_f32_e32 v227, v227
	v_exp_f32_e32 v230, v230
	v_exp_f32_e32 v226, v226
	v_exp_f32_e32 v228, v228
	s_waitcnt lgkmcnt(0)
	v_mfma_f32_32x32x16_bf16 v[82:97], v[66:69], v[142:145], 0
	s_add_i32 s0, 0, 0x16000
	v_exp_f32_e32 v240, v146
	v_add_f32_e32 v146, 0, v229
	v_add_f32_e32 v146, v231, v146
	v_add_f32_e32 v146, v227, v146
	v_add_f32_e32 v146, v230, v146
	v_add_f32_e32 v146, v226, v146
	v_exp_f32_e32 v224, v224
	v_exp_f32_e32 v225, v225
	v_exp_f32_e32 v221, v221
	v_exp_f32_e32 v223, v223
	v_mfma_f32_32x32x16_bf16 v[66:81], v[70:73], v[142:145], 0
	v_exp_f32_e32 v220, v220
	v_exp_f32_e32 v222, v222
	v_add_f32_e32 v146, v228, v146
	v_add_f32_e32 v146, v224, v146
	v_add_f32_e32 v146, v225, v146
	v_add_f32_e32 v146, v221, v146
	v_add_f32_e32 v146, v223, v146
	v_add_f32_e32 v146, v220, v146
	v_add_f32_e32 v146, v222, v146
	v_exp_f32_e32 v217, v217
	v_exp_f32_e32 v219, v219
	v_exp_f32_e32 v216, v216
	v_exp_f32_e32 v218, v218
	v_mfma_f32_32x32x16_bf16 v[82:97], v[206:209], v[138:141], v[82:97]
	v_exp_f32_e32 v164, v164
	v_add_f32_e32 v146, v217, v146
	v_exp_f32_e32 v165, v165
	v_add_f32_e32 v146, v219, v146
	v_exp_f32_e32 v197, v162
	v_add_f32_e32 v146, v216, v146
	v_add_f32_e32 v146, v218, v146
	v_mfma_f32_32x32x16_bf16 v[66:81], v[210:213], v[138:141], v[66:81]
	ds_read_b128 v[206:209], v178 offset:49152
	ds_read_b128 v[210:213], v178 offset:57344
	v_exp_f32_e32 v156, v156
	v_add_f32_e32 v146, v164, v146
	v_exp_f32_e32 v157, v157
	v_add_f32_e32 v146, v165, v146
	v_add_f32_e32 v146, v197, v146
	v_exp_f32_e32 v241, v147
	s_waitcnt lgkmcnt(0)
	v_mfma_f32_32x32x16_bf16 v[82:97], v[206:209], v[134:137], v[82:97]
	v_mfma_f32_32x32x16_bf16 v[66:81], v[210:213], v[134:137], v[66:81]
	ds_read_b128 v[208:211], v180 offset:49152
	ds_read_b128 v[212:215], v180 offset:57344
	s_waitcnt lgkmcnt(0)
	v_mfma_f32_32x32x16_bf16 v[82:97], v[208:211], v[130:133], v[82:97]
	v_mfma_f32_32x32x16_bf16 v[66:81], v[212:215], v[130:133], v[66:81]
	ds_read_b128 v[208:211], v182 offset:49152
	ds_read_b128 v[212:215], v182 offset:57344
	s_waitcnt lgkmcnt(0)
	v_mfma_f32_32x32x16_bf16 v[82:97], v[208:211], v[126:129], v[82:97]
	v_mfma_f32_32x32x16_bf16 v[66:81], v[212:215], v[126:129], v[66:81]
	ds_read_b128 v[210:213], v186 offset:49152
	ds_read_b128 v[232:235], v186 offset:57344
	s_waitcnt lgkmcnt(0)
	v_mfma_f32_32x32x16_bf16 v[82:97], v[210:213], v[122:125], v[82:97]
	v_mfma_f32_32x32x16_bf16 v[66:81], v[232:235], v[122:125], v[66:81]
	ds_read_b128 v[210:213], v188 offset:49152
	ds_read_b128 v[232:235], v188 offset:57344
	s_waitcnt lgkmcnt(0)
	v_mfma_f32_32x32x16_bf16 v[82:97], v[210:213], v[118:121], v[82:97]
	v_mfma_f32_32x32x16_bf16 v[66:81], v[232:235], v[118:121], v[66:81]
	ds_read_b128 v[212:215], v190 offset:49152
	ds_read_b128 v[232:235], v190 offset:57344
	s_waitcnt lgkmcnt(0)
	v_mfma_f32_32x32x16_bf16 v[82:97], v[212:215], v[114:117], v[82:97]
	v_mfma_f32_32x32x16_bf16 v[66:81], v[232:235], v[114:117], v[66:81]
	ds_read_b128 v[212:215], v192 offset:8192
	ds_read_b128 v[232:235], v192 offset:12288
	s_waitcnt lgkmcnt(0)
	v_mfma_f32_32x32x16_bf16 v[82:97], v[212:215], v[110:113], v[82:97]
	v_exp_f32_e32 v215, v163
	s_nop 0
	v_add_f32_e32 v146, v215, v146
	v_mfma_f32_32x32x16_bf16 v[66:81], v[232:235], v[110:113], v[66:81]
	s_lshl_b32 s24, s17, 14
	v_add_u32_e32 v245, s24, v200
	ds_read_b64_tr_b16 v[206:207], v245 offset:0
	ds_read_b64_tr_b16 v[208:209], v245 offset:0x800
	ds_read_b64_tr_b16 v[210:211], v245 offset:0x1000
	ds_read_b64_tr_b16 v[212:213], v245 offset:0x1800
	ds_read_b128 v[232:235], v194 offset:8192
	ds_read_b128 v[236:239], v194 offset:12288
	v_add_f32_e32 v146, v156, v146
	v_add_f32_e32 v146, v157, v146
	s_waitcnt lgkmcnt(0)
	v_mfma_f32_32x32x16_bf16 v[82:97], v[232:235], v[106:109], v[82:97]
	v_mfma_f32_32x32x16_bf16 v[66:81], v[236:239], v[106:109], v[66:81]
	ds_read_b128 v[232:235], v196 offset:8192
	ds_read_b128 v[236:239], v196 offset:12288
	s_waitcnt lgkmcnt(0)
	v_mfma_f32_32x32x16_bf16 v[82:97], v[232:235], v[102:105], v[82:97]
	v_mfma_f32_32x32x16_bf16 v[66:81], v[236:239], v[102:105], v[66:81]
	ds_read_b128 v[232:235], v199 offset:8192
	ds_read_b128 v[236:239], v199 offset:12288
	s_waitcnt lgkmcnt(0)
	v_mfma_f32_32x32x16_bf16 v[82:97], v[232:235], v[98:101], v[82:97]
	v_exp_f32_e32 v232, v154
	v_exp_f32_e32 v233, v155
	v_exp_f32_e32 v234, v152
	v_exp_f32_e32 v235, v153
	v_add_f32_e32 v146, v232, v146
	v_add_f32_e32 v146, v233, v146
	v_add_f32_e32 v146, v234, v146
	v_mfma_f32_32x32x16_bf16 v[66:81], v[236:239], v[98:101], v[66:81]
	v_exp_f32_e32 v236, v150
	v_exp_f32_e32 v237, v151
	v_exp_f32_e32 v238, v148
	v_exp_f32_e32 v239, v149
	v_add_f32_e32 v146, v235, v146
	v_add_f32_e32 v146, v236, v146
	v_add_f32_e32 v146, v237, v146
	v_add_f32_e32 v146, v238, v146
	v_add_f32_e32 v146, v239, v146
	v_add_f32_e32 v146, v240, v146
	v_add_f32_e32 v162, v241, v146
	v_mov_b32_e32 v163, v162
	s_nop 1
	v_permlane32_swap_b32_e32 v162, v163
	v_cvt_pk_bf16_f32 v146, v229, v231
	v_cvt_pk_bf16_f32 v147, v227, v230
	v_cvt_pk_bf16_f32 v148, v226, v228
	v_cvt_pk_bf16_f32 v149, v224, v225
	v_cvt_pk_bf16_f32 v150, v221, v223
	v_cvt_pk_bf16_f32 v151, v220, v222
	v_cvt_pk_bf16_f32 v152, v217, v219
	v_cvt_pk_bf16_f32 v153, v216, v218
	v_cvt_pk_bf16_f32 v154, v164, v165
	v_cvt_pk_bf16_f32 v155, v197, v215
	v_cvt_pk_bf16_f32 v156, v156, v157
	v_cvt_pk_bf16_f32 v157, v232, v233
	v_cvt_pk_bf16_f32 v216, v234, v235
	v_cvt_pk_bf16_f32 v217, v236, v237
	v_cvt_pk_bf16_f32 v218, v238, v239
	v_cvt_pk_bf16_f32 v219, v240, v241
	s_nop 0
	v_permlane32_swap_b32_e32 v146, v148
	v_permlane32_swap_b32_e32 v147, v149
	v_permlane32_swap_b32_e32 v150, v152
	v_permlane32_swap_b32_e32 v151, v153
	v_permlane32_swap_b32_e32 v154, v156
	v_permlane32_swap_b32_e32 v155, v157
	v_permlane32_swap_b32_e32 v216, v218
	v_permlane32_swap_b32_e32 v217, v219
	s_lshl_b32 s24, s17, 14
	v_add_u32_e32 v197, s24, v200
	ds_read_b64_tr_b16 v[228:229], v197 offset:0x2000
	ds_read_b64_tr_b16 v[230:231], v197 offset:0x2800
	ds_read_b64_tr_b16 v[232:233], v197 offset:0x3000
	ds_read_b64_tr_b16 v[234:235], v197 offset:0x3800
	s_nop 0
	v_mfma_f32_32x32x16_bf16 v[2:17], v[146:149], v[206:209], v[2:17]
	ds_read_b64_tr_b16 v[220:221], v197 offset:0x200
	ds_read_b64_tr_b16 v[222:223], v197 offset:0xa00
	v_max_f32_e32 v164, v83, v83
	v_max_f32_e32 v165, v82, v82
	v_max_f32_e32 v164, v165, v164
	v_max3_f32 v164, v164, v84, v85
	v_max3_f32 v164, v164, v86, v87
	v_mfma_f32_32x32x16_bf16 v[2:17], v[150:153], v[210:213], v[2:17]
	ds_read_b64_tr_b16 v[224:225], v197 offset:0x1200
	ds_read_b64_tr_b16 v[226:227], v197 offset:0x1a00
	v_max3_f32 v164, v164, v88, v89
	v_max3_f32 v164, v164, v90, v91
	v_max3_f32 v164, v164, v92, v93
	v_max3_f32 v164, v164, v94, v95
	v_max3_f32 v164, v164, v96, v97
	s_waitcnt lgkmcnt(6)
	v_mfma_f32_32x32x16_bf16 v[2:17], v[154:157], v[228:231], v[2:17]
	ds_read_b64_tr_b16 v[228:229], v197 offset:0x2200
	ds_read_b64_tr_b16 v[230:231], v197 offset:0x2a00
	ds_read_b64_tr_b16 v[236:237], v197 offset:0x3200
	ds_read_b64_tr_b16 v[238:239], v197 offset:0x3a00
	s_waitcnt lgkmcnt(8)
	v_mfma_f32_32x32x16_bf16 v[2:17], v[216:219], v[232:235], v[2:17]
	s_waitcnt lgkmcnt(6)
	v_mfma_f32_32x32x16_bf16 v[50:65], v[146:149], v[220:223], v[50:65]
	v_max3_f32 v164, v164, v66, v67
	v_max3_f32 v164, v164, v68, v69
	v_max3_f32 v164, v164, v70, v71
	v_max3_f32 v164, v164, v72, v73
	v_max3_f32 v164, v164, v74, v75
	v_max3_f32 v164, v164, v76, v77
	v_max3_f32 v164, v164, v78, v79
	s_waitcnt lgkmcnt(4)
	v_mfma_f32_32x32x16_bf16 v[50:65], v[150:153], v[224:227], v[50:65]
	v_max3_f32 v164, v164, v80, v81
	v_mov_b32_e32 v165, v164
	s_nop 1
	v_permlane32_swap_b32_e32 v164, v165
	ds_read_b64_tr_b16 v[220:221], v197 offset:0x400
	v_max_f32_e32 v165, v165, v165
	v_max_f32_e32 v164, v164, v164
	s_waitcnt lgkmcnt(3)
	v_mfma_f32_32x32x16_bf16 v[50:65], v[154:157], v[228:231], v[50:65]
	ds_read_b64_tr_b16 v[222:223], v197 offset:0xc00
	v_max_f32_e32 v164, v164, v165
	v_max_f32_e32 v165, v202, v202
	ds_read_b64_tr_b16 v[224:225], v197 offset:0x1400
	v_max_f32_e32 v165, v165, v164
	ds_read_b64_tr_b16 v[226:227], v197 offset:0x1c00
	v_sub_f32_e32 v215, v164, v202
	s_waitcnt lgkmcnt(4)
	v_mfma_f32_32x32x16_bf16 v[50:65], v[216:219], v[236:239], v[50:65]
	v_sub_f32_e32 v164, v202, v165
	ds_read_b64_tr_b16 v[228:229], v197 offset:0x2400
	v_mul_f32_e32 v164, 0x3dd53b94, v164
	ds_read_b64_tr_b16 v[230:231], v197 offset:0x2c00
	v_exp_f32_e32 v164, v164
	ds_read_b64_tr_b16 v[232:233], v197 offset:0x3400
	v_cmp_ge_f32_e32 vcc, s77, v215
	ds_read_b64_tr_b16 v[234:235], v197 offset:0x3c00
	s_cmp_eq_u64 vcc, exec
	s_cselect_b64 s[4:5], -1, 0
	v_cndmask_b32_e64 v164, v164, 1.0, s[4:5]
	s_waitcnt lgkmcnt(6)
	v_mfma_f32_32x32x16_bf16 v[34:49], v[146:149], v[220:223], v[34:49]
	ds_read_b64_tr_b16 v[220:221], v197 offset:0x600
	ds_read_b64_tr_b16 v[222:223], v197 offset:0xe00
	s_waitcnt lgkmcnt(6)
	v_mfma_f32_32x32x16_bf16 v[34:49], v[150:153], v[224:227], v[34:49]
	ds_read_b64_tr_b16 v[224:225], v197 offset:0x1600
	ds_read_b64_tr_b16 v[226:227], v197 offset:0x1e00
	s_waitcnt lgkmcnt(6)
	v_mfma_f32_32x32x16_bf16 v[34:49], v[154:157], v[228:231], v[34:49]
	ds_read_b64_tr_b16 v[228:229], v197 offset:0x2600
	ds_read_b64_tr_b16 v[230:231], v197 offset:0x2e00
	ds_read_b64_tr_b16 v[236:237], v197 offset:0x3600
	ds_read_b64_tr_b16 v[238:239], v197 offset:0x3e00
	s_waitcnt lgkmcnt(8)
	v_mfma_f32_32x32x16_bf16 v[34:49], v[216:219], v[232:235], v[34:49]
	s_waitcnt lgkmcnt(6)
	v_mfma_f32_32x32x16_bf16 v[18:33], v[146:149], v[220:223], v[18:33]
	v_cmp_gt_f32_e32 vcc, 1.0, v164
	s_waitcnt lgkmcnt(4)
	v_mfma_f32_32x32x16_bf16 v[18:33], v[150:153], v[224:227], v[18:33]
	s_waitcnt lgkmcnt(2)
	v_mfma_f32_32x32x16_bf16 v[18:33], v[154:157], v[228:231], v[18:33]
	s_waitcnt lgkmcnt(0)
	v_mfma_f32_32x32x16_bf16 v[18:33], v[216:219], v[236:239], v[18:33]
	s_cbranch_vccz .LBB0_547
	s_and_saveexec_b64 s[0:1], s[2:3]
	ds_write_b32 v170, v164 offset:128
	s_or_b64 exec, exec, s[0:1]
	s_waitcnt lgkmcnt(0)
	ds_read_b128 v[146:149], v158 offset:224
	ds_read_b128 v[150:153], v158 offset:192
	ds_read_b128 v[154:157], v158 offset:160
	ds_read_b128 v[216:219], v158 offset:128
	s_waitcnt lgkmcnt(0)
	v_pk_mul_f32 v[16:17], v[16:17], v[148:149]
	v_pk_mul_f32 v[12:13], v[12:13], v[152:153]
	v_pk_mul_f32 v[8:9], v[8:9], v[156:157]
	v_pk_mul_f32 v[4:5], v[4:5], v[218:219]
	v_pk_mul_f32 v[14:15], v[14:15], v[146:147]
	v_pk_mul_f32 v[10:11], v[10:11], v[150:151]
	v_pk_mul_f32 v[6:7], v[6:7], v[154:155]
	v_pk_mul_f32 v[2:3], v[2:3], v[216:217]
	v_pk_mul_f32 v[64:65], v[64:65], v[148:149]
	v_pk_mul_f32 v[60:61], v[60:61], v[152:153]
	v_pk_mul_f32 v[56:57], v[56:57], v[156:157]
	v_pk_mul_f32 v[52:53], v[52:53], v[218:219]
	v_pk_mul_f32 v[62:63], v[62:63], v[146:147]
	v_pk_mul_f32 v[58:59], v[58:59], v[150:151]
	v_pk_mul_f32 v[54:55], v[54:55], v[154:155]
	v_pk_mul_f32 v[50:51], v[50:51], v[216:217]
	v_pk_mul_f32 v[48:49], v[48:49], v[148:149]
	v_pk_mul_f32 v[44:45], v[44:45], v[152:153]
	v_pk_mul_f32 v[40:41], v[40:41], v[156:157]
	v_pk_mul_f32 v[36:37], v[36:37], v[218:219]
	v_pk_mul_f32 v[46:47], v[46:47], v[146:147]
	v_pk_mul_f32 v[42:43], v[42:43], v[150:151]
	v_pk_mul_f32 v[38:39], v[38:39], v[154:155]
	v_pk_mul_f32 v[34:35], v[34:35], v[216:217]
	v_pk_mul_f32 v[32:33], v[32:33], v[148:149]
	v_pk_mul_f32 v[28:29], v[28:29], v[152:153]
	v_pk_mul_f32 v[24:25], v[24:25], v[156:157]
	v_pk_mul_f32 v[20:21], v[20:21], v[218:219]
	v_pk_mul_f32 v[30:31], v[30:31], v[146:147]
	v_pk_mul_f32 v[26:27], v[26:27], v[150:151]
	v_pk_mul_f32 v[22:23], v[22:23], v[154:155]
	v_pk_mul_f32 v[18:19], v[18:19], v[216:217]

.LBB0_549:
	v_cndmask_b32_e64 v165, v165, v202, s[4:5]
	v_mul_f32_e32 v154, 0xbdd53b94, v165
	v_fmamk_f32 v202, v69, 0x3dd53b94, v154
	v_fmamk_f32 v215, v70, 0x3dd53b94, v154
	v_fmamk_f32 v155, v66, 0x3dd53b94, v154
	v_fmamk_f32 v156, v67, 0x3dd53b94, v154
	v_fmamk_f32 v157, v68, 0x3dd53b94, v154
	v_fmamk_f32 v216, v71, 0x3dd53b94, v154
	v_fmamk_f32 v217, v72, 0x3dd53b94, v154
	v_fmamk_f32 v218, v73, 0x3dd53b94, v154
	ds_read_b128 v[66:69], v174 offset:32768
	ds_read_b128 v[70:73], v174 offset:40960
	ds_read_b128 v[146:149], v176 offset:32768
	ds_read_b128 v[150:153], v176 offset:40960
	s_cmp_lg_u32 s98, 0
	s_cbranch_scc1 .Lattn_mla_nopf
	s_add_u32 s0, s38, s20
	s_addc_u32 s1, s39, s21
	s_add_u32 s100, s0, s42
	s_addc_u32 s101, s1, s43
	s_mov_b32 m0, s93
	v_lshl_add_u64 v[254:255], v[246:247], 0, s[100:101]
	global_load_lds_dwordx4 v[254:255], off
	s_add_u32 s100, s0, s46
	s_addc_u32 s101, s1, s47
	s_mov_b32 m0, s94
	v_lshl_add_u64 v[254:255], v[246:247], 0, s[100:101]
	global_load_lds_dwordx4 v[254:255], off
	s_add_u32 s100, s0, s44
	s_addc_u32 s101, s1, s45
	s_add_i32 s98, s89, s24
	s_mov_b32 m0, s98
	v_lshl_add_u64 v[254:255], v[248:249], 0, s[100:101]
	global_load_lds_dwordx4 v[254:255], off
	s_add_u32 s100, s0, s50
	s_addc_u32 s101, s1, s51
	s_add_i32 m0, s98, 0x2000
	v_lshl_add_u64 v[254:255], v[248:249], 0, s[100:101]
	global_load_lds_dwordx4 v[254:255], off
	s_add_u32 s0, s38, s88
	s_addc_u32 s1, s39, s87
	s_add_u32 s0, s0, s58
	s_addc_u32 s1, s1, s59
	s_mov_b32 m0, s95
	v_lshl_add_u64 v[254:255], v[250:251], 0, s[0:1]
	global_load_lds_dwordx4 v[254:255], off
.Lattn_mla_nopf:
	v_fmamk_f32 v224, v82, 0x3dd53b94, v154
	v_fmamk_f32 v225, v83, 0x3dd53b94, v154
	v_fmamk_f32 v226, v84, 0x3dd53b94, v154
	v_fmamk_f32 v227, v85, 0x3dd53b94, v154
	v_fmamk_f32 v228, v86, 0x3dd53b94, v154
	v_fmamk_f32 v229, v87, 0x3dd53b94, v154
	v_fmamk_f32 v230, v88, 0x3dd53b94, v154
	v_fmamk_f32 v231, v89, 0x3dd53b94, v154
	v_fmamk_f32 v234, v90, 0x3dd53b94, v154
	v_fmamk_f32 v235, v91, 0x3dd53b94, v154
	v_fmamk_f32 v236, v92, 0x3dd53b94, v154
	v_fmamk_f32 v237, v93, 0x3dd53b94, v154
	v_fmamk_f32 v238, v94, 0x3dd53b94, v154
	v_fmamk_f32 v239, v95, 0x3dd53b94, v154
	v_fmamk_f32 v240, v96, 0x3dd53b94, v154
	v_fmamk_f32 v241, v97, 0x3dd53b94, v154
	s_waitcnt lgkmcnt(0)
	v_mfma_f32_32x32x16_bf16 v[82:97], v[66:69], v[142:145], 0
	v_fmamk_f32 v232, v79, 0x3dd53b94, v154
	v_fmamk_f32 v233, v80, 0x3dd53b94, v154
	v_fmamk_f32 v219, v74, 0x3dd53b94, v154
	v_fmamk_f32 v220, v75, 0x3dd53b94, v154
	v_fmamk_f32 v221, v76, 0x3dd53b94, v154
	v_fmamk_f32 v222, v77, 0x3dd53b94, v154
	v_fmamk_f32 v223, v78, 0x3dd53b94, v154
	v_fmac_f32_e32 v154, 0x3dd53b94, v81
	v_mfma_f32_32x32x16_bf16 v[66:81], v[70:73], v[142:145], 0
	v_exp_f32_e32 v224, v224
	v_exp_f32_e32 v225, v225
	v_exp_f32_e32 v226, v226
	v_add_f32_e32 v245, 0, v224
	v_add_f32_e32 v245, v225, v245
	v_add_f32_e32 v245, v226, v245
	v_mfma_f32_32x32x16_bf16 v[82:97], v[146:149], v[138:141], v[82:97]
	v_exp_f32_e32 v227, v227
	v_exp_f32_e32 v228, v228
	v_add_f32_e32 v245, v227, v245
	v_add_f32_e32 v245, v228, v245
	v_mfma_f32_32x32x16_bf16 v[66:81], v[150:153], v[138:141], v[66:81]
	ds_read_b128 v[146:149], v178 offset:32768
	ds_read_b128 v[150:153], v178 offset:40960
	v_exp_f32_e32 v229, v229
	v_exp_f32_e32 v230, v230
	v_add_f32_e32 v245, v229, v245
	v_add_f32_e32 v245, v230, v245
	s_waitcnt lgkmcnt(0)
	v_mfma_f32_32x32x16_bf16 v[82:97], v[146:149], v[134:137], v[82:97]
	v_mfma_f32_32x32x16_bf16 v[66:81], v[150:153], v[134:137], v[66:81]
	ds_read_b128 v[146:149], v180 offset:32768
	ds_read_b128 v[150:153], v180 offset:40960
	v_exp_f32_e32 v231, v231
	v_exp_f32_e32 v234, v234
	v_exp_f32_e32 v235, v235
	v_add_f32_e32 v245, v231, v245
	v_add_f32_e32 v245, v234, v245
	v_add_f32_e32 v245, v235, v245
	s_waitcnt lgkmcnt(0)
	v_mfma_f32_32x32x16_bf16 v[82:97], v[146:149], v[130:133], v[82:97]
	v_mfma_f32_32x32x16_bf16 v[66:81], v[150:153], v[130:133], v[66:81]
	ds_read_b128 v[146:149], v182 offset:32768
	ds_read_b128 v[150:153], v182 offset:40960
	v_exp_f32_e32 v236, v236
	v_exp_f32_e32 v237, v237
	v_exp_f32_e32 v238, v238
	v_add_f32_e32 v245, v236, v245
	v_add_f32_e32 v245, v237, v245
	v_add_f32_e32 v245, v238, v245
	s_waitcnt lgkmcnt(0)
	v_mfma_f32_32x32x16_bf16 v[82:97], v[146:149], v[126:129], v[82:97]
	v_mfma_f32_32x32x16_bf16 v[66:81], v[150:153], v[126:129], v[66:81]
	ds_read_b128 v[146:149], v186 offset:32768
	ds_read_b128 v[150:153], v186 offset:40960
	v_exp_f32_e32 v239, v239
	v_exp_f32_e32 v240, v240
	v_exp_f32_e32 v241, v241
	v_add_f32_e32 v245, v239, v245
	v_add_f32_e32 v245, v240, v245
	v_add_f32_e32 v245, v241, v245
	s_waitcnt lgkmcnt(0)
	v_mfma_f32_32x32x16_bf16 v[82:97], v[146:149], v[122:125], v[82:97]
	v_mfma_f32_32x32x16_bf16 v[66:81], v[150:153], v[122:125], v[66:81]
	ds_read_b128 v[146:149], v188 offset:32768
	ds_read_b128 v[150:153], v188 offset:40960
	v_exp_f32_e32 v155, v155
	v_exp_f32_e32 v156, v156
	v_exp_f32_e32 v157, v157
	v_add_f32_e32 v245, v155, v245
	v_add_f32_e32 v245, v156, v245
	v_add_f32_e32 v245, v157, v245
	s_waitcnt lgkmcnt(0)
	v_mfma_f32_32x32x16_bf16 v[82:97], v[146:149], v[118:121], v[82:97]
	v_mfma_f32_32x32x16_bf16 v[66:81], v[150:153], v[118:121], v[66:81]
	ds_read_b128 v[146:149], v190 offset:32768
	ds_read_b128 v[150:153], v190 offset:40960
	v_exp_f32_e32 v202, v202
	v_exp_f32_e32 v215, v215
	v_exp_f32_e32 v216, v216
	v_add_f32_e32 v245, v202, v245
	v_add_f32_e32 v245, v215, v245
	v_add_f32_e32 v245, v216, v245
	s_waitcnt lgkmcnt(0)
	v_mfma_f32_32x32x16_bf16 v[82:97], v[146:149], v[114:117], v[82:97]
	v_mfma_f32_32x32x16_bf16 v[66:81], v[150:153], v[114:117], v[66:81]
	ds_read_b128 v[146:149], v192
	ds_read_b128 v[150:153], v192 offset:4096
	v_exp_f32_e32 v217, v217
	v_exp_f32_e32 v218, v218
	v_exp_f32_e32 v219, v219
	v_add_f32_e32 v245, v217, v245
	v_add_f32_e32 v245, v218, v245
	v_add_f32_e32 v245, v219, v245
	s_waitcnt lgkmcnt(0)
	v_mfma_f32_32x32x16_bf16 v[82:97], v[146:149], v[110:113], v[82:97]
	v_mfma_f32_32x32x16_bf16 v[66:81], v[150:153], v[110:113], v[66:81]
	ds_read_b128 v[146:149], v194
	ds_read_b128 v[150:153], v194 offset:4096
	v_exp_f32_e32 v220, v220
	v_exp_f32_e32 v221, v221
	v_exp_f32_e32 v222, v222
	v_add_f32_e32 v245, v220, v245
	v_add_f32_e32 v245, v221, v245
	v_add_f32_e32 v245, v222, v245
	s_waitcnt lgkmcnt(0)
	v_mfma_f32_32x32x16_bf16 v[82:97], v[146:149], v[106:109], v[82:97]
	v_mfma_f32_32x32x16_bf16 v[66:81], v[150:153], v[106:109], v[66:81]
	ds_read_b128 v[146:149], v196
	ds_read_b128 v[150:153], v196 offset:4096
	v_exp_f32_e32 v223, v223
	v_exp_f32_e32 v242, v232
	v_exp_f32_e32 v243, v233
	v_add_f32_e32 v245, v223, v245
	v_add_f32_e32 v245, v242, v245
	v_add_f32_e32 v245, v243, v245
	s_waitcnt lgkmcnt(0)
	v_mfma_f32_32x32x16_bf16 v[82:97], v[146:149], v[102:105], v[82:97]
	v_mfma_f32_32x32x16_bf16 v[66:81], v[150:153], v[102:105], v[66:81]
	ds_read_b128 v[146:149], v199
	ds_read_b128 v[150:153], v199 offset:4096
	v_lshl_add_u32 v214, s23, 14, v200
	ds_read_b64_tr_b16 v[206:207], v214 offset:0
	ds_read_b64_tr_b16 v[208:209], v214 offset:0x800
	ds_read_b64_tr_b16 v[210:211], v214 offset:0x1000
	ds_read_b64_tr_b16 v[212:213], v214 offset:0x1800
	v_exp_f32_e32 v244, v154
	s_waitcnt lgkmcnt(4)
	v_mfma_f32_32x32x16_bf16 v[82:97], v[146:149], v[98:101], v[82:97]
	v_mfma_f32_32x32x16_bf16 v[66:81], v[150:153], v[98:101], v[66:81]
	v_add_f32_e32 v232, v244, v245
	v_mov_b32_e32 v233, v232
	s_nop 1
	v_permlane32_swap_b32_e32 v232, v233
	v_cvt_pk_bf16_f32 v146, v224, v225
	v_cvt_pk_bf16_f32 v147, v226, v227
	v_cvt_pk_bf16_f32 v148, v228, v229
	v_cvt_pk_bf16_f32 v149, v230, v231
	v_cvt_pk_bf16_f32 v150, v234, v235
	v_cvt_pk_bf16_f32 v151, v236, v237
	v_cvt_pk_bf16_f32 v152, v238, v239
	v_cvt_pk_bf16_f32 v153, v240, v241
	v_cvt_pk_bf16_f32 v154, v155, v156
	v_cvt_pk_bf16_f32 v155, v157, v202
	v_cvt_pk_bf16_f32 v156, v215, v216
	v_cvt_pk_bf16_f32 v157, v217, v218
	v_cvt_pk_bf16_f32 v216, v219, v220
	v_cvt_pk_bf16_f32 v217, v221, v222
	v_cvt_pk_bf16_f32 v218, v223, v242
	v_cvt_pk_bf16_f32 v219, v243, v244
	s_nop 0
	v_permlane32_swap_b32_e32 v146, v148
	v_permlane32_swap_b32_e32 v147, v149
	v_permlane32_swap_b32_e32 v150, v152
	v_permlane32_swap_b32_e32 v151, v153
	v_permlane32_swap_b32_e32 v154, v156
	v_permlane32_swap_b32_e32 v155, v157
	v_permlane32_swap_b32_e32 v216, v218
	v_permlane32_swap_b32_e32 v217, v219
	ds_read_b64_tr_b16 v[228:229], v214 offset:0x2000
	ds_read_b64_tr_b16 v[230:231], v214 offset:0x2800
	ds_read_b64_tr_b16 v[234:235], v214 offset:0x3000
	ds_read_b64_tr_b16 v[236:237], v214 offset:0x3800
	s_nop 0
	s_waitcnt lgkmcnt(6)
	v_mfma_f32_32x32x16_bf16 v[2:17], v[146:149], v[206:209], v[2:17]
	ds_read_b64_tr_b16 v[220:221], v214 offset:0x200
	ds_read_b64_tr_b16 v[222:223], v214 offset:0xa00
	v_max_f32_e32 v202, v83, v83
	v_max_f32_e32 v215, v82, v82
	v_max_f32_e32 v202, v215, v202
	v_max3_f32 v202, v202, v84, v85
	v_max3_f32 v202, v202, v86, v87
	s_waitcnt lgkmcnt(6)
	v_mfma_f32_32x32x16_bf16 v[2:17], v[150:153], v[210:213], v[2:17]
	ds_read_b64_tr_b16 v[224:225], v214 offset:0x1200
	ds_read_b64_tr_b16 v[226:227], v214 offset:0x1a00
	v_max3_f32 v202, v202, v88, v89
	v_max3_f32 v202, v202, v90, v91
	v_max3_f32 v202, v202, v92, v93
	v_max3_f32 v202, v202, v94, v95
	v_max3_f32 v202, v202, v96, v97
	s_waitcnt lgkmcnt(6)
	v_mfma_f32_32x32x16_bf16 v[2:17], v[154:157], v[228:231], v[2:17]
	ds_read_b64_tr_b16 v[228:229], v214 offset:0x2200
	ds_read_b64_tr_b16 v[230:231], v214 offset:0x2a00
	ds_read_b64_tr_b16 v[238:239], v214 offset:0x3200
	ds_read_b64_tr_b16 v[240:241], v214 offset:0x3a00
	s_waitcnt lgkmcnt(8)
	v_mfma_f32_32x32x16_bf16 v[2:17], v[216:219], v[234:237], v[2:17]
	s_waitcnt lgkmcnt(6)
	v_mfma_f32_32x32x16_bf16 v[50:65], v[146:149], v[220:223], v[50:65]
	v_max3_f32 v202, v202, v66, v67
	v_max3_f32 v202, v202, v68, v69
	v_max3_f32 v202, v202, v70, v71
	v_max3_f32 v202, v202, v72, v73
	v_max3_f32 v202, v202, v74, v75
	v_max3_f32 v202, v202, v76, v77
	v_max3_f32 v202, v202, v78, v79
	s_waitcnt lgkmcnt(4)
	v_mfma_f32_32x32x16_bf16 v[50:65], v[150:153], v[224:227], v[50:65]
	v_max3_f32 v202, v202, v80, v81
	v_mov_b32_e32 v215, v202
	s_nop 1
	v_permlane32_swap_b32_e32 v202, v215
	v_max_f32_e32 v215, v215, v215
	v_max_f32_e32 v202, v202, v202
	v_max_f32_e32 v202, v202, v215
	v_max_f32_e32 v220, v165, v165
	v_sub_f32_e32 v215, v202, v165
	v_max_f32_e32 v202, v220, v202
	v_sub_f32_e32 v220, v165, v202
	v_mul_f32_e32 v220, 0x3dd53b94, v220
	s_waitcnt lgkmcnt(2)
	v_mfma_f32_32x32x16_bf16 v[50:65], v[154:157], v[228:231], v[50:65]
	v_exp_f32_e32 v220, v220
	v_cmp_ge_f32_e32 vcc, s77, v215
	s_cmp_eq_u64 vcc, exec
	s_cselect_b64 s[4:5], -1, 0
	v_cndmask_b32_e64 v215, v220, 1.0, s[4:5]
	ds_read_b64_tr_b16 v[220:221], v214 offset:0x400
	ds_read_b64_tr_b16 v[222:223], v214 offset:0xc00
	ds_read_b64_tr_b16 v[224:225], v214 offset:0x1400
	s_waitcnt lgkmcnt(3)
	v_mfma_f32_32x32x16_bf16 v[50:65], v[216:219], v[238:241], v[50:65]
	ds_read_b64_tr_b16 v[226:227], v214 offset:0x1c00
	ds_read_b64_tr_b16 v[228:229], v214 offset:0x2400
	ds_read_b64_tr_b16 v[230:231], v214 offset:0x2c00
	ds_read_b64_tr_b16 v[234:235], v214 offset:0x3400
	ds_read_b64_tr_b16 v[236:237], v214 offset:0x3c00
	s_waitcnt lgkmcnt(6)
	v_mfma_f32_32x32x16_bf16 v[34:49], v[146:149], v[220:223], v[34:49]
	ds_read_b64_tr_b16 v[220:221], v214 offset:0x600
	ds_read_b64_tr_b16 v[222:223], v214 offset:0xe00
	s_waitcnt lgkmcnt(6)
	v_mfma_f32_32x32x16_bf16 v[34:49], v[150:153], v[224:227], v[34:49]
	ds_read_b64_tr_b16 v[224:225], v214 offset:0x1600
	ds_read_b64_tr_b16 v[226:227], v214 offset:0x1e00
	s_waitcnt lgkmcnt(6)
	v_mfma_f32_32x32x16_bf16 v[34:49], v[154:157], v[228:231], v[34:49]
	ds_read_b64_tr_b16 v[228:229], v214 offset:0x2600
	ds_read_b64_tr_b16 v[230:231], v214 offset:0x2e00
	ds_read_b64_tr_b16 v[238:239], v214 offset:0x3600
	ds_read_b64_tr_b16 v[240:241], v214 offset:0x3e00
	s_waitcnt lgkmcnt(8)
	v_mfma_f32_32x32x16_bf16 v[34:49], v[216:219], v[234:237], v[34:49]
	s_waitcnt lgkmcnt(6)
	v_mfma_f32_32x32x16_bf16 v[18:33], v[146:149], v[220:223], v[18:33]
	v_cmp_gt_f32_e32 vcc, 1.0, v215
	s_waitcnt lgkmcnt(4)
	v_mfma_f32_32x32x16_bf16 v[18:33], v[150:153], v[224:227], v[18:33]
	s_waitcnt lgkmcnt(2)
	v_mfma_f32_32x32x16_bf16 v[18:33], v[154:157], v[228:231], v[18:33]
	s_waitcnt lgkmcnt(0)
	v_mfma_f32_32x32x16_bf16 v[18:33], v[216:219], v[238:241], v[18:33]
	s_cbranch_vccz .LBB0_553
	s_and_saveexec_b64 s[0:1], s[2:3]
	ds_write_b32 v170, v215 offset:128
	s_or_b64 exec, exec, s[0:1]
	s_waitcnt lgkmcnt(0)
	ds_read_b128 v[146:149], v158 offset:224
	ds_read_b128 v[150:153], v158 offset:192
	ds_read_b128 v[154:157], v158 offset:160
	ds_read_b128 v[216:219], v158 offset:128
	s_waitcnt lgkmcnt(0)
	v_pk_mul_f32 v[16:17], v[16:17], v[148:149]
	v_pk_mul_f32 v[12:13], v[12:13], v[152:153]
	v_pk_mul_f32 v[8:9], v[8:9], v[156:157]
	v_pk_mul_f32 v[4:5], v[4:5], v[218:219]
	v_pk_mul_f32 v[14:15], v[14:15], v[146:147]
	v_pk_mul_f32 v[10:11], v[10:11], v[150:151]
	v_pk_mul_f32 v[6:7], v[6:7], v[154:155]
	v_pk_mul_f32 v[2:3], v[2:3], v[216:217]
	v_pk_mul_f32 v[64:65], v[64:65], v[148:149]
	v_pk_mul_f32 v[60:61], v[60:61], v[152:153]
	v_pk_mul_f32 v[56:57], v[56:57], v[156:157]
	v_pk_mul_f32 v[52:53], v[52:53], v[218:219]
	v_pk_mul_f32 v[62:63], v[62:63], v[146:147]
	v_pk_mul_f32 v[58:59], v[58:59], v[150:151]
	v_pk_mul_f32 v[54:55], v[54:55], v[154:155]
	v_pk_mul_f32 v[50:51], v[50:51], v[216:217]
	v_pk_mul_f32 v[48:49], v[48:49], v[148:149]
	v_pk_mul_f32 v[44:45], v[44:45], v[152:153]
	v_pk_mul_f32 v[40:41], v[40:41], v[156:157]
	v_pk_mul_f32 v[36:37], v[36:37], v[218:219]
	v_pk_mul_f32 v[46:47], v[46:47], v[146:147]
	v_pk_mul_f32 v[42:43], v[42:43], v[150:151]
	v_pk_mul_f32 v[38:39], v[38:39], v[154:155]
	v_pk_mul_f32 v[34:35], v[34:35], v[216:217]
	v_pk_mul_f32 v[32:33], v[32:33], v[148:149]
	v_pk_mul_f32 v[28:29], v[28:29], v[152:153]
	v_pk_mul_f32 v[24:25], v[24:25], v[156:157]
	v_pk_mul_f32 v[20:21], v[20:21], v[218:219]
	v_pk_mul_f32 v[30:31], v[30:31], v[146:147]
	v_pk_mul_f32 v[26:27], v[26:27], v[150:151]
	v_pk_mul_f32 v[22:23], v[22:23], v[154:155]
	v_pk_mul_f32 v[18:19], v[18:19], v[216:217]
